# first seam uses the XCD-hierarchical device barrier instead of the cooperative-groups grid sync (same release/acquire semantics)
# speedup vs baseline: 1.0295x; 1.0114x over previous
; #define LAS __attribute__((address_space(3)))
; __global__ void __launch_bounds__(512) mega(Params Pval) {
;     ...
;         if (step == 0) grid.sync();
;         else if (step != NSTEP - 1) xcd_barrier((unsigned*)ws, (volatile LAS unsigned*)(lds + LDS_MAIN), I);
.LBB0_730:
	s_branch .LBB0_31
